# nt also on gla_pass1 z loads and rg_d3 AU/PH/z loads (once-read streams)
# baseline (speedup 1.0000x reference)
; __device__ __forceinline__ void gla_pass1(const Ctx& cx, const Params& p, int l, int item, float* ldsf, int lane) {
;   int n = item % 36, t = item / 36;
;   int dir = t & 1; t >>= 1;
;   int h = t & 7; t >>= 3;
;   int b = t & 3, m = t >> 2;
;   int tb = dir == 0 ? n : (n < 4 ? 3 - n : 39 - n);
;   const float* z = reinterpret_cast<const float*>(p.ws + OFF_Z);
;   const int rowbase = b * TPB + tb * 64;
;   const int hc = h * 64 + lane;
;   const int c = lane & 15, g = lane >> 4;
;   const float lb = (m == 0) ? lower_bound(p, l, dir, hc) : 0.f;
;   const float fconst = 1.f - exp2f(-5.f - (float)h);
;   const int c0off = (m == 0) ? (dir ? 1024 : 512) : 3072;
;   const int c1off = (m == 0) ? 1536 : 3584;
;   char* L = reinterpret_cast<char*>(ldsf);
;   bfu* KTs = reinterpret_cast<bfu*>(L + 4352);
;   bfu* VTs = reinterpret_cast<bfu*>(L + 6912);
;   float* gs = reinterpret_cast<float*>(L + 9472);
;   f32x4 T[4][4];
; #pragma unroll
;   for (int db = 0; db < 4; ++db)
; #pragma unroll
;     for (int vb = 0; vb < 4; ++vb) T[db][vb] = (f32x4){0.f, 0.f, 0.f, 0.f};
;   float gacc = 1.f;
;   float r0[16], r1[16];
; #pragma unroll
;   for (int i = 0; i < 16; ++i) {
;     int tok = dir ? 63 - i : i;
;     const float* zr = z + (size_t)(rowbase + tok) * INW;
;     r0[i] = zr[c0off + hc];
;     r1[i] = zr[c1off + hc];
;   }
.LBB0_109:
	v_lshl_or_b32 v124, v130, 2, v131
	v_mul_hi_i32 v0, v124, s48
	v_lshrrev_b32_e32 v1, 31, v0
	v_ashrrev_i32_e32 v0, 3, v0
	v_add_u32_e32 v0, v0, v1
	v_bfe_u32 v4, v0, 1, 3
	v_cvt_f32_ubyte0_e32 v6, v4
	v_sub_f32_e32 v6, 0xc0a00000, v6
	s_mov_b32 s0, 0xc2fc0000
	v_cmp_gt_f32_e64 s[0:1], s0, v6
	v_mul_lo_u32 v1, v0, 36
	v_sub_u32_e32 v1, v124, v1
	v_cndmask_b32_e64 v7, 0, v183, s[0:1]
	v_add_f32_e32 v6, v6, v7
	v_exp_f32_e32 v6, v6
	v_cmp_lt_i32_e32 vcc, 3, v1
	v_and_b32_e32 v3, 1, v0
	v_bfe_i32 v2, v0, 0, 1
	v_cndmask_b32_e64 v5, 3, 39, vcc
	v_sub_u32_e32 v5, v5, v1
	v_cmp_eq_u32_e32 vcc, 0, v3
	v_cndmask_b32_e64 v3, 0, v184, s[0:1]
	v_cmp_gt_u32_e64 s[38:39], 64, v0
	v_bfe_u32 v0, v0, 4, 2
	v_cndmask_b32_e32 v1, v5, v1, vcc
	v_ldexp_f32 v9, v6, v3
	v_mov_b32_e32 v3, 0x400
	v_mov_b32_e32 v5, 0x200
	v_mul_u32_u24_e32 v0, 0x900, v0
	v_cndmask_b32_e32 v3, v3, v5, vcc
	v_lshl_add_u32 v119, v1, 6, v0
	s_waitcnt vmcnt(25)
	v_cndmask_b32_e64 v11, 61, 2, vcc
	v_cndmask_b32_e64 v3, v185, v3, s[38:39]
	v_lshl_or_b32 v0, v4, 6, v132
	v_cndmask_b32_e64 v1, v181, v182, s[38:39]
	v_or_b32_e32 v11, v119, v11
	v_or_b32_e32 v8, v3, v0
	v_or_b32_e32 v10, v0, v1
	v_and_or_b32 v0, v2, 63, v119
	v_cndmask_b32_e64 v4, 62, 1, vcc
	v_mul_lo_u32 v16, v11, s25
	v_cndmask_b32_e64 v11, 60, 3, vcc
	v_mul_lo_u32 v0, v0, s25
	v_or_b32_e32 v4, v119, v4
	v_or_b32_e32 v11, v119, v11
	v_ashrrev_i32_e32 v1, 31, v0
	v_mul_lo_u32 v4, v4, s25
	v_ashrrev_i32_e32 v17, 31, v16
	v_mul_lo_u32 v24, v11, s25
	v_lshl_add_u64 v[0:1], v[0:1], 2, s[22:23]
	s_waitcnt vmcnt(23)
	v_lshlrev_b32_e32 v12, 2, v8
	s_waitcnt vmcnt(21)
	v_mov_b32_e32 v13, v18
	s_waitcnt vmcnt(19)
	v_lshlrev_b32_e32 v14, 2, v10
	s_waitcnt vmcnt(17)
; __device__ __forceinline__ void gla_pass1(const Ctx& cx, const Params& p, int l, int item, float* ldsf, int lane) {
;     ...
;   float gacc = 1.f;
;   float r0[16], r1[16];
; #pragma unroll
;   for (int i = 0; i < 16; ++i) {
;     int tok = dir ? 63 - i : i;
;     const float* zr = z + (size_t)(rowbase + tok) * INW;
;     r0[i] = zr[c0off + hc];
;     r1[i] = zr[c1off + hc];
;   }
	v_mov_b32_e32 v15, v18
	v_ashrrev_i32_e32 v5, 31, v4
	v_lshl_add_u64 v[16:17], v[16:17], 2, s[22:23]
	v_ashrrev_i32_e32 v25, 31, v24
	v_cndmask_b32_e64 v11, 58, 5, vcc
	v_lshl_add_u64 v[2:3], v[0:1], 0, v[12:13]
	v_lshl_add_u64 v[0:1], v[0:1], 0, v[14:15]
	v_lshl_add_u64 v[4:5], v[4:5], 2, s[22:23]
	v_lshl_add_u64 v[22:23], v[16:17], 0, v[12:13]
	v_lshl_add_u64 v[16:17], v[16:17], 0, v[14:15]
	v_lshl_add_u64 v[24:25], v[24:25], 2, s[22:23]
	v_or_b32_e32 v11, v119, v11
	v_lshl_add_u64 v[6:7], v[4:5], 0, v[12:13]
	v_lshl_add_u64 v[4:5], v[4:5], 0, v[14:15]
	v_lshl_add_u64 v[26:27], v[24:25], 0, v[12:13]
	v_lshl_add_u64 v[24:25], v[24:25], 0, v[14:15]
	global_load_dword v121, v[2:3], off nt
	s_nop 0
	global_load_dword v0, v[0:1], off nt
	s_nop 0
	global_load_dword v123, v[6:7], off nt
	global_load_dword v1, v[4:5], off nt
	global_load_dword v125, v[22:23], off nt
	global_load_dword v2, v[16:17], off nt
	global_load_dword v138, v[26:27], off nt
	global_load_dword v3, v[24:25], off nt
	v_mul_lo_u32 v16, v11, s25
	v_cndmask_b32_e64 v11, 57, 6, vcc
	v_cndmask_b32_e64 v4, 59, 4, vcc
	v_or_b32_e32 v11, v119, v11
	v_or_b32_e32 v4, v119, v4
	v_mul_lo_u32 v24, v11, s25
	v_cndmask_b32_e64 v11, 56, 7, vcc
	v_mul_lo_u32 v4, v4, s25
	v_or_b32_e32 v11, v119, v11
	v_ashrrev_i32_e32 v5, 31, v4
	v_ashrrev_i32_e32 v17, 31, v16
	v_mul_lo_u32 v28, v11, s25
	v_lshl_add_u64 v[4:5], v[4:5], 2, s[22:23]
	v_lshl_add_u64 v[16:17], v[16:17], 2, s[22:23]
	v_ashrrev_i32_e32 v25, 31, v24
	v_ashrrev_i32_e32 v29, 31, v28
	v_cndmask_b32_e64 v11, 55, 8, vcc
	v_lshl_add_u64 v[6:7], v[4:5], 0, v[12:13]
	v_lshl_add_u64 v[4:5], v[4:5], 0, v[14:15]
	v_lshl_add_u64 v[22:23], v[16:17], 0, v[12:13]
	v_lshl_add_u64 v[16:17], v[16:17], 0, v[14:15]
	v_lshl_add_u64 v[24:25], v[24:25], 2, s[22:23]
	v_lshl_add_u64 v[28:29], v[28:29], 2, s[22:23]
	v_or_b32_e32 v11, v119, v11
	v_lshl_add_u64 v[26:27], v[24:25], 0, v[12:13]
	v_lshl_add_u64 v[24:25], v[24:25], 0, v[14:15]
	v_lshl_add_u64 v[30:31], v[28:29], 0, v[12:13]
	v_lshl_add_u64 v[28:29], v[28:29], 0, v[14:15]
	global_load_dword v139, v[6:7], off nt
	s_nop 0
	global_load_dword v4, v[4:5], off nt
	s_nop 0
	global_load_dword v141, v[22:23], off nt
	global_load_dword v5, v[16:17], off nt
	global_load_dword v142, v[26:27], off nt
	global_load_dword v6, v[24:25], off nt
	global_load_dword v143, v[30:31], off nt
	global_load_dword v7, v[28:29], off nt
	v_mul_lo_u32 v16, v11, s25
	v_cndmask_b32_e64 v11, 54, 9, vcc
	v_or_b32_e32 v11, v119, v11
	v_mul_lo_u32 v22, v11, s25
	v_ashrrev_i32_e32 v23, 31, v22
	v_cndmask_b32_e64 v11, 53, 10, vcc
	v_lshl_add_u64 v[22:23], v[22:23], 2, s[22:23]
	v_or_b32_e32 v11, v119, v11
	v_lshl_add_u64 v[86:87], v[22:23], 0, v[12:13]
	v_lshl_add_u64 v[88:89], v[22:23], 0, v[14:15]
	v_mul_lo_u32 v22, v11, s25
	v_ashrrev_i32_e32 v23, 31, v22
	v_cndmask_b32_e64 v11, 52, 11, vcc
	v_lshl_add_u64 v[22:23], v[22:23], 2, s[22:23]
	v_or_b32_e32 v11, v119, v11
	v_lshl_add_u64 v[90:91], v[22:23], 0, v[12:13]
	v_lshl_add_u64 v[92:93], v[22:23], 0, v[14:15]
	v_mul_lo_u32 v22, v11, s25
	v_ashrrev_i32_e32 v23, 31, v22
	v_cndmask_b32_e64 v11, 51, 12, vcc
	v_lshl_add_u64 v[22:23], v[22:23], 2, s[22:23]
	v_or_b32_e32 v11, v119, v11
	v_lshl_add_u64 v[94:95], v[22:23], 0, v[12:13]
	v_lshl_add_u64 v[96:97], v[22:23], 0, v[14:15]
	v_mul_lo_u32 v22, v11, s25
	v_ashrrev_i32_e32 v23, 31, v22
	v_cndmask_b32_e64 v11, 50, 13, vcc
	v_lshl_add_u64 v[22:23], v[22:23], 2, s[22:23]
	v_or_b32_e32 v11, v119, v11
	v_lshl_add_u64 v[24:25], v[22:23], 0, v[12:13]
	v_lshl_add_u64 v[98:99], v[22:23], 0, v[14:15]
	v_mul_lo_u32 v22, v11, s25
	v_ashrrev_i32_e32 v23, 31, v22
	v_cndmask_b32_e64 v11, 49, 14, vcc
	v_lshl_add_u64 v[22:23], v[22:23], 2, s[22:23]
	v_or_b32_e32 v11, v119, v11
	v_lshl_add_u64 v[26:27], v[22:23], 0, v[12:13]
	v_lshl_add_u64 v[100:101], v[22:23], 0, v[14:15]
	v_mul_lo_u32 v22, v11, s25
	v_ashrrev_i32_e32 v23, 31, v22
	v_cndmask_b32_e64 v11, 48, 15, vcc
	v_lshl_add_u64 v[22:23], v[22:23], 2, s[22:23]
	v_or_b32_e32 v11, v119, v11
	v_lshl_add_u64 v[28:29], v[22:23], 0, v[12:13]
	v_lshl_add_u64 v[102:103], v[22:23], 0, v[14:15]
	v_mul_lo_u32 v22, v11, s25
	v_ashrrev_i32_e32 v17, 31, v16
	v_ashrrev_i32_e32 v23, 31, v22
	v_lshl_add_u64 v[16:17], v[16:17], 2, s[22:23]
	v_lshl_add_u64 v[22:23], v[22:23], 2, s[22:23]
	v_lshl_add_u64 v[84:85], v[16:17], 0, v[12:13]
	v_lshl_add_u64 v[12:13], v[22:23], 0, v[12:13]
	global_load_dword v144, v[24:25], off nt
	global_load_dword v145, v[26:27], off nt
	global_load_dword v147, v[28:29], off nt
	global_load_dword v127, v[12:13], off nt
	v_lshl_add_u64 v[12:13], v[22:23], 0, v[14:15]
	v_lshl_add_u64 v[16:17], v[16:17], 0, v[14:15]
	v_sub_f32_e32 v140, 1.0, v9
	v_lshlrev_b32_e32 v126, 2, v8
	v_lshlrev_b32_e32 v128, 2, v10
	global_load_dword v146, v[84:85], off nt
	global_load_dword v153, v[86:87], off nt
	global_load_dword v154, v[90:91], off nt
	global_load_dword v155, v[94:95], off nt
	global_load_dword v11, v[96:97], off nt
	global_load_dword v10, v[92:93], off nt
	global_load_dword v9, v[88:89], off nt
	global_load_dword v8, v[16:17], off nt
	global_load_dword v15, v[12:13], off nt
	global_load_dword v14, v[102:103], off nt
	s_nop 0
	global_load_dword v13, v[100:101], off nt
	global_load_dword v12, v[98:99], off nt
	v_mov_b32_e32 v20, 0
	s_mov_b32 s2, 31
	v_mov_b32_e32 v137, 1.0
	s_mov_b32 s0, 32
	v_mov_b32_e32 v21, v20
	v_mov_b32_e32 v22, v20
	v_mov_b32_e32 v23, v20
	v_mov_b32_e32 v24, v20
	v_mov_b32_e32 v25, v20
	v_mov_b32_e32 v26, v20
	v_mov_b32_e32 v27, v20
	v_mov_b32_e32 v28, v20
	v_mov_b32_e32 v29, v20
	v_mov_b32_e32 v30, v20
	v_mov_b32_e32 v31, v20
	v_mov_b32_e32 v32, v20
	v_mov_b32_e32 v33, v20
	v_mov_b32_e32 v34, v20
	v_mov_b32_e32 v35, v20
	v_mov_b32_e32 v36, v20
	v_mov_b32_e32 v37, v20
	v_mov_b32_e32 v38, v20
	v_mov_b32_e32 v39, v20
	v_mov_b32_e32 v56, v20
	v_mov_b32_e32 v57, v20
	v_mov_b32_e32 v58, v20
	v_mov_b32_e32 v59, v20
	v_mov_b32_e32 v60, v20
	v_mov_b32_e32 v61, v20
	v_mov_b32_e32 v62, v20
	v_mov_b32_e32 v63, v20
	v_mov_b32_e32 v64, v20
	v_mov_b32_e32 v65, v20
	v_mov_b32_e32 v66, v20
	v_mov_b32_e32 v67, v20
	v_mov_b32_e32 v68, v20
	v_mov_b32_e32 v69, v20
	v_mov_b32_e32 v70, v20
	v_mov_b32_e32 v71, v20
	v_mov_b32_e32 v72, v20
	v_mov_b32_e32 v73, v20
	v_mov_b32_e32 v74, v20
	v_mov_b32_e32 v75, v20
	v_mov_b32_e32 v76, v20
	v_mov_b32_e32 v77, v20
	v_mov_b32_e32 v78, v20
	v_mov_b32_e32 v79, v20
	v_mov_b32_e32 v80, v20
	v_mov_b32_e32 v81, v20
	v_mov_b32_e32 v82, v20
	v_mov_b32_e32 v83, v20
	v_mov_b32_e32 v52, v20
	v_mov_b32_e32 v53, v20
	v_mov_b32_e32 v54, v20
	v_mov_b32_e32 v55, v20
	v_mov_b32_e32 v48, v20
	v_mov_b32_e32 v49, v20
	v_mov_b32_e32 v50, v20
	v_mov_b32_e32 v51, v20
	v_mov_b32_e32 v44, v20
	v_mov_b32_e32 v45, v20
	v_mov_b32_e32 v46, v20
	v_mov_b32_e32 v47, v20
	v_mov_b32_e32 v40, v20
	v_mov_b32_e32 v41, v20
	v_mov_b32_e32 v42, v20
	v_mov_b32_e32 v43, v20
	s_branch .LBB0_111

; __device__ __forceinline__ void gla_pass1(const Ctx& cx, const Params& p, int l, int item, float* ldsf, int lane) {
;     ...
;       float kt[16];
;       float e = 1.f;
; #pragma unroll
;       for (int i = 0; i < 16; ++i) {
;         float f, k;
;         if (m == 0) { f = r0[i]; k = 1.f - f; }
;         else { f = fconst; k = r0[i]; }
;         e = fmaxf(e * f, 1e-26f);
;         kt[i] = k * __builtin_amdgcn_rcpf(e);
;       }
;       const float gdec = e;
;       gacc *= gdec;
;       gs[lane] = gdec;
; #pragma unroll
;       for (int q = 0; q < 4; ++q) {
;         u32x2 kk, vv;
;         kk.x = pack2(kt[4 * q] * gdec, kt[4 * q + 1] * gdec); kk.y = pack2(kt[4 * q + 2] * gdec, kt[4 * q + 3] * gdec);
;         vv.x = pack2(r1[4 * q], r1[4 * q + 1]); vv.y = pack2(r1[4 * q + 2], r1[4 * q + 3]);
;         *reinterpret_cast<u32x2*>(KTs + lane * 20 + 4 * q) = kk;
;         *reinterpret_cast<u32x2*>(VTs + lane * 20 + 4 * q) = vv;
;       }
;     }
.LBB0_111:
	s_waitcnt vmcnt(31)
	v_cndmask_b32_e64 v17, v140, v121, s[38:39]
	v_max_f32_e32 v17, v17, v17
	v_max_f32_e32 v17, 0x14461206, v17
	v_rcp_f32_e32 v19, v17
	v_sub_f32_e32 v16, 1.0, v121
	v_cndmask_b32_e64 v16, v121, v16, s[38:39]
	s_cmp_eq_u32 s0, -16
	v_mul_f32_e32 v16, v16, v19
	s_waitcnt vmcnt(29)
	v_cndmask_b32_e64 v19, v140, v123, s[38:39]
	v_mul_f32_e32 v17, v19, v17
	v_max_f32_e32 v17, 0x14461206, v17
	v_rcp_f32_e32 v84, v17
	v_sub_f32_e32 v19, 1.0, v123
	v_cndmask_b32_e64 v19, v123, v19, s[38:39]
	v_mul_f32_e32 v84, v19, v84
	s_waitcnt vmcnt(27)
	v_cndmask_b32_e64 v19, v140, v125, s[38:39]
	v_mul_f32_e32 v17, v19, v17
	v_max_f32_e32 v17, 0x14461206, v17
	v_rcp_f32_e32 v85, v17
	v_sub_f32_e32 v19, 1.0, v125
	v_cndmask_b32_e64 v19, v125, v19, s[38:39]
	v_mul_f32_e32 v85, v19, v85
	s_waitcnt vmcnt(25)
	v_cndmask_b32_e64 v19, v140, v138, s[38:39]
	v_mul_f32_e32 v17, v19, v17
	v_max_f32_e32 v17, 0x14461206, v17
	v_rcp_f32_e32 v86, v17
	v_sub_f32_e32 v19, 1.0, v138
	v_cndmask_b32_e64 v19, v138, v19, s[38:39]
	v_mul_f32_e32 v86, v19, v86
	s_waitcnt vmcnt(23)
	v_cndmask_b32_e64 v19, v140, v139, s[38:39]
	v_mul_f32_e32 v17, v19, v17
	v_max_f32_e32 v87, 0x14461206, v17
	s_waitcnt vmcnt(21)
	v_cndmask_b32_e64 v17, v140, v141, s[38:39]
	v_mul_f32_e32 v17, v17, v87
	v_max_f32_e32 v88, 0x14461206, v17
	s_waitcnt vmcnt(19)
	v_cndmask_b32_e64 v17, v140, v142, s[38:39]
	v_mul_f32_e32 v17, v17, v88
	v_max_f32_e32 v89, 0x14461206, v17
	s_waitcnt vmcnt(17)
	v_cndmask_b32_e64 v17, v140, v143, s[38:39]
	v_mul_f32_e32 v17, v17, v89
	v_max_f32_e32 v90, 0x14461206, v17
	s_waitcnt vmcnt(11)
	v_cndmask_b32_e64 v17, v140, v146, s[38:39]
	v_mul_f32_e32 v17, v17, v90
	v_max_f32_e32 v91, 0x14461206, v17
	s_waitcnt vmcnt(10)
	v_cndmask_b32_e64 v17, v140, v153, s[38:39]
	v_mul_f32_e32 v17, v17, v91
	v_max_f32_e32 v92, 0x14461206, v17
	s_waitcnt vmcnt(9)
	v_cndmask_b32_e64 v17, v140, v154, s[38:39]
	v_mul_f32_e32 v17, v17, v92
	v_max_f32_e32 v93, 0x14461206, v17
	s_waitcnt vmcnt(8)
	v_cndmask_b32_e64 v17, v140, v155, s[38:39]
	v_mul_f32_e32 v17, v17, v93
	v_max_f32_e32 v94, 0x14461206, v17
	s_waitcnt vmcnt(7)
	v_cndmask_b32_e64 v17, v140, v144, s[38:39]
	v_mul_f32_e32 v17, v17, v94
	v_max_f32_e32 v95, 0x14461206, v17
	s_waitcnt vmcnt(5)
	v_cndmask_b32_e64 v17, v140, v145, s[38:39]
	v_mul_f32_e32 v17, v17, v95
	v_max_f32_e32 v96, 0x14461206, v17
	s_waitcnt vmcnt(3)
	v_cndmask_b32_e64 v17, v140, v147, s[38:39]
	v_mul_f32_e32 v17, v17, v96
	v_max_f32_e32 v97, 0x14461206, v17
	s_waitcnt vmcnt(1)
	v_cndmask_b32_e64 v17, v140, v127, s[38:39]
	v_mul_f32_e32 v17, v17, v97
	v_max_f32_e32 v19, 0x14461206, v17
	v_mul_f32_e32 v16, v16, v19
	v_mul_f32_e32 v17, v84, v19
	v_cvt_pk_bf16_f32 v16, v16, v17
	v_mul_f32_e32 v17, v85, v19
	v_mul_f32_e32 v84, v86, v19
	v_cvt_pk_bf16_f32 v17, v17, v84
	v_rcp_f32_e32 v84, v87
	v_sub_f32_e32 v85, 1.0, v139
	v_cndmask_b32_e64 v85, v139, v85, s[38:39]
	v_sub_f32_e32 v86, 1.0, v141
	v_mul_f32_e32 v84, v85, v84
	v_rcp_f32_e32 v85, v88
	v_cndmask_b32_e64 v86, v141, v86, s[38:39]
	v_sub_f32_e32 v87, 1.0, v142
	v_cndmask_b32_e64 v87, v142, v87, s[38:39]
	v_mul_f32_e32 v85, v86, v85
	v_rcp_f32_e32 v86, v89
	v_sub_f32_e32 v88, 1.0, v143
	v_cndmask_b32_e64 v88, v143, v88, s[38:39]
	v_mul_f32_e32 v84, v84, v19
	v_mul_f32_e32 v86, v87, v86
	v_rcp_f32_e32 v87, v90
	v_mul_f32_e32 v85, v85, v19
	v_cvt_pk_bf16_f32 v84, v84, v85
	v_mul_f32_e32 v85, v86, v19
	v_mul_f32_e32 v87, v88, v87
	v_mul_f32_e32 v86, v87, v19
	v_cvt_pk_bf16_f32 v85, v85, v86
	v_add_u32_e32 v86, 0x1100, v113
	ds_write_b32 v133, v19 offset:9472
	ds_write2_b64 v86, v[16:17], v[84:85] offset1:1
	v_cvt_pk_bf16_f32 v16, v0, v1
	v_cvt_pk_bf16_f32 v17, v2, v3
	v_cvt_pk_bf16_f32 v84, v4, v5
	v_cvt_pk_bf16_f32 v85, v6, v7
	v_add_u32_e32 v86, 0x1b00, v113
	ds_write2_b64 v86, v[16:17], v[84:85] offset1:1
	v_rcp_f32_e32 v16, v91
	v_sub_f32_e32 v17, 1.0, v146
	v_cndmask_b32_e64 v17, v146, v17, s[38:39]
	v_sub_f32_e32 v84, 1.0, v153
	v_mul_f32_e32 v16, v17, v16
	v_rcp_f32_e32 v17, v92
	v_cndmask_b32_e64 v84, v153, v84, s[38:39]
	v_sub_f32_e32 v85, 1.0, v154
	v_cndmask_b32_e64 v85, v154, v85, s[38:39]
	v_mul_f32_e32 v17, v84, v17
	v_rcp_f32_e32 v84, v93
	v_sub_f32_e32 v86, 1.0, v155
	v_cndmask_b32_e64 v86, v155, v86, s[38:39]
	v_mul_f32_e32 v16, v16, v19
	v_mul_f32_e32 v84, v85, v84
	v_rcp_f32_e32 v85, v94
	v_mul_f32_e32 v17, v17, v19
	v_cvt_pk_bf16_f32 v16, v16, v17
	v_mul_f32_e32 v17, v84, v19
	v_mul_f32_e32 v85, v86, v85
	v_mul_f32_e32 v84, v85, v19
	v_cvt_pk_bf16_f32 v17, v17, v84
	v_rcp_f32_e32 v84, v95
	v_sub_f32_e32 v85, 1.0, v144
	v_cndmask_b32_e64 v85, v144, v85, s[38:39]
	v_sub_f32_e32 v86, 1.0, v145
	v_mul_f32_e32 v84, v85, v84
	v_rcp_f32_e32 v85, v96
	v_cndmask_b32_e64 v86, v145, v86, s[38:39]
	v_sub_f32_e32 v87, 1.0, v147
	v_rcp_f32_e32 v88, v19
	v_mul_f32_e32 v85, v86, v85
	v_rcp_f32_e32 v86, v97
	v_cndmask_b32_e64 v87, v147, v87, s[38:39]
	v_mul_f32_e32 v84, v84, v19
	v_mul_f32_e32 v85, v85, v19
	v_mul_f32_e32 v86, v87, v86
	v_sub_f32_e32 v87, 1.0, v127
	v_cndmask_b32_e64 v87, v127, v87, s[38:39]
	v_mul_f32_e32 v87, v87, v88
	v_cvt_pk_bf16_f32 v84, v84, v85
	v_mul_f32_e32 v85, v19, v86
	v_mul_f32_e32 v86, v19, v87
	v_cvt_pk_bf16_f32 v85, v85, v86
	v_add_u32_e32 v86, 0x1110, v113
	ds_write2_b64 v86, v[16:17], v[84:85] offset1:1
	s_waitcnt vmcnt(4)
	v_cvt_pk_bf16_f32 v16, v8, v9
	v_cvt_pk_bf16_f32 v17, v10, v11
	s_waitcnt vmcnt(0)
	v_cvt_pk_bf16_f32 v84, v12, v13
	v_cvt_pk_bf16_f32 v85, v14, v15
	v_add_u32_e32 v86, 0x1b10, v113
	ds_write2_b64 v86, v[16:17], v[84:85] offset1:1
	s_cbranch_scc1 .LBB0_110
; __device__ __forceinline__ void gla_pass1(const Ctx& cx, const Params& p, int l, int item, float* ldsf, int lane) {
;     ...
;     if (sub < 3) {
; #pragma unroll
;       for (int i = 0; i < 16; ++i) {
;         int s = (sub + 1) * 16 + i;
;         int tok = dir ? 63 - s : s;
;         const float* zr = z + (size_t)(rowbase + tok) * INW;
;         r0[i] = zr[c0off + hc];
;         r1[i] = zr[c1off + hc];
;       }
;     }
	s_add_i32 s1, s2, -15
	s_add_i32 s3, s0, 15
	v_mov_b32_e32 v0, s3
	v_mov_b32_e32 v1, s1
	v_cndmask_b32_e32 v0, v0, v1, vcc
	v_add_u32_e32 v0, v0, v119
	v_mov_b64_e32 v[16:17], s[22:23]
	v_mad_i64_i32 v[0:1], s[6:7], v0, s54, v[16:17]
	v_mov_b32_e32 v127, v18
	v_mov_b32_e32 v129, v18
	v_lshl_add_u64 v[2:3], v[0:1], 0, v[126:127]
	v_lshl_add_u64 v[0:1], v[0:1], 0, v[128:129]
	s_add_i32 s1, s2, -14
	s_add_i32 s3, s0, 14
	global_load_dword v121, v[2:3], off nt
	s_nop 0
	global_load_dword v0, v[0:1], off nt
	v_mov_b32_e32 v1, s3
	v_mov_b32_e32 v2, s1
	v_cndmask_b32_e32 v1, v1, v2, vcc
	v_add_u32_e32 v1, v1, v119
	v_mad_i64_i32 v[2:3], s[6:7], v1, s54, v[16:17]
	v_lshl_add_u64 v[4:5], v[2:3], 0, v[126:127]
	v_lshl_add_u64 v[2:3], v[2:3], 0, v[128:129]
	s_add_i32 s1, s2, -13
	s_add_i32 s3, s0, 13
	global_load_dword v123, v[4:5], off nt
	global_load_dword v1, v[2:3], off nt
	v_mov_b32_e32 v2, s3
	v_mov_b32_e32 v3, s1
	v_cndmask_b32_e32 v2, v2, v3, vcc
	v_add_u32_e32 v2, v2, v119
	v_mad_i64_i32 v[2:3], s[6:7], v2, s54, v[16:17]
	v_lshl_add_u64 v[4:5], v[2:3], 0, v[126:127]
	v_lshl_add_u64 v[2:3], v[2:3], 0, v[128:129]
	s_add_i32 s1, s2, -12
	s_add_i32 s3, s0, 12
	global_load_dword v125, v[4:5], off nt
	s_nop 0
	global_load_dword v2, v[2:3], off nt
	v_mov_b32_e32 v3, s3
	v_mov_b32_e32 v4, s1
	v_cndmask_b32_e32 v3, v3, v4, vcc
	v_add_u32_e32 v3, v3, v119
	v_mad_i64_i32 v[4:5], s[6:7], v3, s54, v[16:17]
	v_lshl_add_u64 v[6:7], v[4:5], 0, v[126:127]
	v_lshl_add_u64 v[4:5], v[4:5], 0, v[128:129]
	s_add_i32 s1, s2, -11
	s_add_i32 s3, s0, 11
	global_load_dword v138, v[6:7], off nt
	global_load_dword v3, v[4:5], off nt
	v_mov_b32_e32 v4, s3
	v_mov_b32_e32 v5, s1
	v_cndmask_b32_e32 v4, v4, v5, vcc
	v_add_u32_e32 v4, v4, v119
	v_mad_i64_i32 v[4:5], s[6:7], v4, s54, v[16:17]
	v_lshl_add_u64 v[6:7], v[4:5], 0, v[126:127]
	v_lshl_add_u64 v[4:5], v[4:5], 0, v[128:129]
	s_add_i32 s1, s2, -10
	s_add_i32 s3, s0, 10
	global_load_dword v139, v[6:7], off nt
	s_nop 0
	global_load_dword v4, v[4:5], off nt
	v_mov_b32_e32 v5, s3
	v_mov_b32_e32 v6, s1
	v_cndmask_b32_e32 v5, v5, v6, vcc
	v_add_u32_e32 v5, v5, v119
	v_mad_i64_i32 v[6:7], s[6:7], v5, s54, v[16:17]
	v_lshl_add_u64 v[8:9], v[6:7], 0, v[126:127]
	v_lshl_add_u64 v[6:7], v[6:7], 0, v[128:129]
	s_add_i32 s1, s2, -9
	s_add_i32 s3, s0, 9
	global_load_dword v141, v[8:9], off nt
	global_load_dword v5, v[6:7], off nt
	v_mov_b32_e32 v6, s3
	v_mov_b32_e32 v7, s1
	v_cndmask_b32_e32 v6, v6, v7, vcc
	v_add_u32_e32 v6, v6, v119
	v_mad_i64_i32 v[6:7], s[6:7], v6, s54, v[16:17]
	v_lshl_add_u64 v[8:9], v[6:7], 0, v[126:127]
	v_lshl_add_u64 v[6:7], v[6:7], 0, v[128:129]
	s_add_i32 s1, s2, -8
	s_add_i32 s3, s0, 8
	global_load_dword v142, v[8:9], off nt
	s_nop 0
	global_load_dword v6, v[6:7], off nt
	v_mov_b32_e32 v7, s3
	v_mov_b32_e32 v8, s1
	v_cndmask_b32_e32 v7, v7, v8, vcc
	v_add_u32_e32 v7, v7, v119
	v_mad_i64_i32 v[8:9], s[6:7], v7, s54, v[16:17]
	v_lshl_add_u64 v[10:11], v[8:9], 0, v[126:127]
	v_lshl_add_u64 v[8:9], v[8:9], 0, v[128:129]
	s_add_i32 s1, s2, -7
	s_add_i32 s3, s0, 7
	global_load_dword v143, v[10:11], off nt
	global_load_dword v7, v[8:9], off nt
	v_mov_b32_e32 v8, s3
	v_mov_b32_e32 v9, s1
	v_cndmask_b32_e32 v8, v8, v9, vcc
	v_add_u32_e32 v8, v8, v119
	v_mad_i64_i32 v[8:9], s[6:7], v8, s54, v[16:17]
	v_lshl_add_u64 v[10:11], v[8:9], 0, v[126:127]
	v_lshl_add_u64 v[8:9], v[8:9], 0, v[128:129]
	s_add_i32 s1, s2, -6
	s_add_i32 s3, s0, 6
	global_load_dword v146, v[10:11], off nt
	s_nop 0
	global_load_dword v8, v[8:9], off nt
	v_mov_b32_e32 v9, s3
	v_mov_b32_e32 v10, s1
	v_cndmask_b32_e32 v9, v9, v10, vcc
	v_add_u32_e32 v9, v9, v119
	v_mad_i64_i32 v[10:11], s[6:7], v9, s54, v[16:17]
	v_lshl_add_u64 v[12:13], v[10:11], 0, v[126:127]
	v_lshl_add_u64 v[10:11], v[10:11], 0, v[128:129]
	s_add_i32 s1, s2, -5
	s_add_i32 s3, s0, 5
	global_load_dword v153, v[12:13], off nt
	global_load_dword v9, v[10:11], off nt
	v_mov_b32_e32 v10, s3
	v_mov_b32_e32 v11, s1
	v_cndmask_b32_e32 v10, v10, v11, vcc
	v_add_u32_e32 v10, v10, v119
	v_mad_i64_i32 v[10:11], s[6:7], v10, s54, v[16:17]
	v_lshl_add_u64 v[12:13], v[10:11], 0, v[126:127]
	v_lshl_add_u64 v[10:11], v[10:11], 0, v[128:129]
	s_add_i32 s1, s2, -4
	s_add_i32 s3, s0, 4
	global_load_dword v154, v[12:13], off nt
	s_nop 0
	global_load_dword v10, v[10:11], off nt
	v_mov_b32_e32 v11, s3
	v_mov_b32_e32 v12, s1
	v_cndmask_b32_e32 v11, v11, v12, vcc
	v_add_u32_e32 v11, v11, v119
	v_mad_i64_i32 v[12:13], s[6:7], v11, s54, v[16:17]
	v_lshl_add_u64 v[14:15], v[12:13], 0, v[126:127]
	v_lshl_add_u64 v[12:13], v[12:13], 0, v[128:129]
	s_add_i32 s1, s2, -3
	s_add_i32 s3, s0, 3
	global_load_dword v155, v[14:15], off nt
	global_load_dword v11, v[12:13], off nt
	v_mov_b32_e32 v12, s3
	v_mov_b32_e32 v13, s1
	v_cndmask_b32_e32 v12, v12, v13, vcc
	v_add_u32_e32 v12, v12, v119
	v_mad_i64_i32 v[12:13], s[6:7], v12, s54, v[16:17]
	v_lshl_add_u64 v[14:15], v[12:13], 0, v[126:127]
	v_lshl_add_u64 v[12:13], v[12:13], 0, v[128:129]
	s_add_i32 s1, s2, -2
	s_add_i32 s3, s0, 2
	global_load_dword v144, v[14:15], off nt
	s_nop 0
	global_load_dword v12, v[12:13], off nt
	v_mov_b32_e32 v13, s3
	v_mov_b32_e32 v14, s1
	v_cndmask_b32_e32 v13, v13, v14, vcc
	v_add_u32_e32 v13, v13, v119
	v_mad_i64_i32 v[14:15], s[6:7], v13, s54, v[16:17]
	v_lshl_add_u64 v[84:85], v[14:15], 0, v[126:127]
	v_lshl_add_u64 v[14:15], v[14:15], 0, v[128:129]
	s_add_i32 s1, s2, -1
	s_add_i32 s3, s0, 1
	global_load_dword v145, v[84:85], off nt
	global_load_dword v13, v[14:15], off nt
	v_mov_b32_e32 v14, s3
	v_mov_b32_e32 v15, s1
	v_cndmask_b32_e32 v14, v14, v15, vcc
	v_add_u32_e32 v14, v14, v119
	v_mad_i64_i32 v[14:15], s[6:7], v14, s54, v[16:17]
	v_lshl_add_u64 v[84:85], v[14:15], 0, v[126:127]
	v_lshl_add_u64 v[14:15], v[14:15], 0, v[128:129]
	global_load_dword v147, v[84:85], off nt
	s_nop 0
	global_load_dword v14, v[14:15], off nt
	v_mov_b32_e32 v15, s0
	v_mov_b32_e32 v84, s2
	v_cndmask_b32_e32 v15, v15, v84, vcc
	v_add_u32_e32 v15, v15, v119
	v_mad_i64_i32 v[16:17], s[6:7], v15, s54, v[16:17]
	v_lshl_add_u64 v[84:85], v[16:17], 0, v[126:127]
	v_lshl_add_u64 v[16:17], v[16:17], 0, v[128:129]
	global_load_dword v127, v[84:85], off nt
	global_load_dword v15, v[16:17], off nt
	s_branch .LBB0_110

; __device__ __forceinline__ void rg_d3(const Ctx& cx, const Params& p, int l, int idx) {
;     ...
;   int ch = idx & 511, rg = idx >> 9;
;   int b = rg / 144, tb16 = rg % 144;
;   if (l == 1 && tb16 < 16) return;
;   int row0 = b * TPB + tb16 * 16;
;   float hf[16];
;   float h = PH[((size_t)(b * 2 + 0) * 144 + tb16) * 512 + ch].y;
; #pragma unroll
;   for (int i = 0; i < 16; ++i) {
;     float2 au = AU[((size_t)(row0 + i)) * 512 + ch];
;     h = au.x * h + au.y;
;     hf[i] = h;
;   }
;   int n = tb16 < 16 ? 15 - tb16 : 159 - tb16;
;   h = PH[((size_t)(b * 2 + 1) * 144 + n) * 512 + ch].y;
.LBB0_140:
	v_ashrrev_i32_e32 v0, 1, v19
	v_mul_hi_i32 v1, v0, s48
	v_lshrrev_b32_e32 v2, 31, v1
	v_ashrrev_i32_e32 v1, 5, v1
	v_add_u32_e32 v1, v1, v2
	s_movk_i32 s7, 0x90
	v_mul_lo_u32 v2, v1, s7
	v_sub_u32_e32 v62, v0, v2
	v_readlane_b32 s10, v255, 5
	v_cmp_gt_i32_e32 vcc, 16, v62
	v_readlane_b32 s11, v255, 6
	s_and_b64 s[10:11], s[10:11], vcc
	s_xor_b64 s[10:11], s[10:11], -1
	s_and_saveexec_b64 s[14:15], s[10:11]
	s_cbranch_execz .LBB0_139
	s_movk_i32 s7, 0x120
	v_mul_lo_u32 v63, v1, s7
	v_lshlrev_b32_e32 v12, 4, v0
	v_add_u32_e32 v0, v63, v62
	v_and_or_b32 v110, v85, s94, v84
	v_ashrrev_i32_e32 v1, 31, v0
	v_readlane_b32 s10, v252, 31
	v_readlane_b32 s20, v252, 33
	v_or_b32_e32 v30, 1, v12
	v_or_b32_e32 v40, 2, v12
	v_or_b32_e32 v52, 3, v12
	v_lshlrev_b64 v[0:1], 12, v[0:1]
	v_readlane_b32 s11, v252, 32
	v_lshlrev_b32_e32 v66, 3, v110
	v_mov_b32_e32 v67, v18
	v_readlane_b32 s21, v252, 34
	v_ashrrev_i32_e32 v31, 31, v30
	v_ashrrev_i32_e32 v41, 31, v40
	v_ashrrev_i32_e32 v53, 31, v52
	v_lshl_add_u64 v[0:1], s[10:11], 0, v[0:1]
	v_lshl_add_u64 v[72:73], s[20:21], 0, v[66:67]
	v_lshlrev_b64 v[4:5], 12, v[30:31]
	v_lshlrev_b64 v[8:9], 12, v[40:41]
	v_lshlrev_b64 v[14:15], 12, v[52:53]
	v_lshl_add_u64 v[0:1], v[0:1], 0, v[66:67]
	v_ashrrev_i32_e32 v13, 31, v12
	v_lshl_add_u64 v[6:7], v[72:73], 0, v[4:5]
	v_lshl_add_u64 v[10:11], v[72:73], 0, v[8:9]
	v_lshl_add_u64 v[16:17], v[72:73], 0, v[14:15]
	global_load_dword v111, v[0:1], off offset:4 nt
	v_or_b32_e32 v60, 4, v12
	global_load_dwordx2 v[6:7], v[6:7], off nt
	v_ashrrev_i32_e32 v61, 31, v60
	global_load_dwordx2 v[10:11], v[10:11], off nt
	v_or_b32_e32 v64, 5, v12
	global_load_dwordx2 v[16:17], v[16:17], off nt
	v_lshlrev_b64 v[0:1], 12, v[12:13]
	v_lshl_add_u64 v[22:23], v[72:73], 0, v[0:1]
	global_load_dwordx2 v[2:3], v[22:23], off nt
	v_lshlrev_b64 v[20:21], 12, v[60:61]
	v_ashrrev_i32_e32 v65, 31, v64
	v_or_b32_e32 v68, 6, v12
	v_lshl_add_u64 v[24:25], v[72:73], 0, v[20:21]
	v_lshlrev_b64 v[26:27], 12, v[64:65]
	v_ashrrev_i32_e32 v69, 31, v68
	v_or_b32_e32 v70, 7, v12
	global_load_dwordx2 v[24:25], v[24:25], off nt
	v_lshl_add_u64 v[28:29], v[72:73], 0, v[26:27]
	v_lshlrev_b64 v[32:33], 12, v[68:69]
	v_ashrrev_i32_e32 v71, 31, v70
	v_or_b32_e32 v74, 8, v12
	global_load_dwordx2 v[28:29], v[28:29], off nt
	v_lshl_add_u64 v[34:35], v[72:73], 0, v[32:33]
	v_lshlrev_b64 v[36:37], 12, v[70:71]
	v_ashrrev_i32_e32 v75, 31, v74
	v_or_b32_e32 v76, 9, v12
	global_load_dwordx2 v[34:35], v[34:35], off nt
	v_lshl_add_u64 v[38:39], v[72:73], 0, v[36:37]
	v_lshlrev_b64 v[42:43], 12, v[74:75]
	v_ashrrev_i32_e32 v77, 31, v76
	v_or_b32_e32 v78, 10, v12
	v_cndmask_b32_e64 v13, v187, 15, vcc
	v_sub_u32_e32 v31, v63, v62
	s_movk_i32 s7, 0x90
	global_load_dwordx2 v[38:39], v[38:39], off nt
	v_lshl_add_u64 v[44:45], v[72:73], 0, v[42:43]
	v_lshlrev_b64 v[46:47], 12, v[76:77]
	v_ashrrev_i32_e32 v79, 31, v78
	v_or_b32_e32 v82, 11, v12
	v_add3_u32 v62, v31, v13, s7
	global_load_dwordx2 v[44:45], v[44:45], off nt
	v_lshl_add_u64 v[48:49], v[72:73], 0, v[46:47]
	v_lshlrev_b64 v[50:51], 12, v[78:79]
	v_ashrrev_i32_e32 v83, 31, v82
	v_or_b32_e32 v80, 12, v12
	v_ashrrev_i32_e32 v63, 31, v62
	global_load_dwordx2 v[48:49], v[48:49], off nt
	v_lshl_add_u64 v[54:55], v[72:73], 0, v[50:51]
	v_lshlrev_b64 v[56:57], 12, v[82:83]
	v_ashrrev_i32_e32 v81, 31, v80
	v_or_b32_e32 v90, 13, v12
	v_lshlrev_b64 v[62:63], 12, v[62:63]
	global_load_dwordx2 v[54:55], v[54:55], off nt
	v_lshl_add_u64 v[58:59], v[72:73], 0, v[56:57]
	v_lshlrev_b64 v[86:87], 12, v[80:81]
	v_ashrrev_i32_e32 v91, 31, v90
	v_or_b32_e32 v96, 14, v12
	v_lshl_add_u64 v[62:63], s[10:11], 0, v[62:63]
	global_load_dwordx2 v[58:59], v[58:59], off nt
	v_lshl_add_u64 v[88:89], v[72:73], 0, v[86:87]
	v_lshlrev_b64 v[92:93], 12, v[90:91]
	v_ashrrev_i32_e32 v97, 31, v96
	v_or_b32_e32 v102, 15, v12
	v_lshl_add_u64 v[62:63], v[62:63], 0, v[66:67]
	v_readlane_b32 s10, v252, 35
	global_load_dwordx2 v[88:89], v[88:89], off nt
	v_lshl_add_u64 v[94:95], v[72:73], 0, v[92:93]
	v_lshlrev_b64 v[98:99], 12, v[96:97]
	v_ashrrev_i32_e32 v103, 31, v102
	global_load_dword v13, v[62:63], off offset:4 nt
	v_lshlrev_b32_e32 v62, 2, v110
	v_mov_b32_e32 v63, v18
	v_readlane_b32 s11, v252, 36
	s_mov_b32 s7, 0x240f000
	global_load_dwordx2 v[94:95], v[94:95], off nt
	v_lshl_add_u64 v[100:101], v[72:73], 0, v[98:99]
	v_lshlrev_b64 v[104:105], 12, v[102:103]
	v_lshl_add_u64 v[66:67], s[10:11], 0, v[62:63]
	v_add_co_u32_e32 v62, vcc, s7, v22
	global_load_dwordx2 v[100:101], v[100:101], off nt
	v_lshl_add_u64 v[72:73], v[72:73], 0, v[104:105]
	v_addc_co_u32_e32 v63, vcc, 0, v23, vcc
	global_load_dwordx2 v[106:107], v[72:73], off nt
	global_load_dwordx2 v[108:109], v[62:63], off nt
	v_mad_i64_i32 v[62:63], s[10:11], v102, s54, v[66:67]
	s_mov_b32 s7, 0x240e000
	global_load_dword v31, v[62:63], off nt
	v_add_co_u32_e32 v62, vcc, s7, v22
	s_mov_b32 s7, 0x240d000
	s_nop 0
	v_addc_co_u32_e32 v63, vcc, 0, v23, vcc
	global_load_dwordx2 v[102:103], v[62:63], off nt
	v_mad_i64_i32 v[62:63], s[10:11], v96, s54, v[66:67]
	global_load_dword v41, v[62:63], off nt
	v_add_co_u32_e32 v62, vcc, s7, v22
	s_mov_b32 s7, 0x240c000
	s_nop 0
	v_addc_co_u32_e32 v63, vcc, 0, v23, vcc
	global_load_dwordx2 v[96:97], v[62:63], off nt
	v_mad_i64_i32 v[62:63], s[10:11], v90, s54, v[66:67]
	global_load_dword v53, v[62:63], off nt
	v_add_co_u32_e32 v62, vcc, s7, v22
	s_waitcnt vmcnt(19)
	v_fmac_f32_e32 v3, v111, v2
	v_addc_co_u32_e32 v63, vcc, 0, v23, vcc
	global_load_dwordx2 v[72:73], v[62:63], off nt
	v_mad_i64_i32 v[62:63], s[10:11], v80, s54, v[66:67]
	global_load_dword v61, v[62:63], off nt
	v_fmac_f32_e32 v7, v3, v6
	v_fmac_f32_e32 v11, v7, v10
	v_fmac_f32_e32 v17, v11, v16
	s_waitcnt vmcnt(20)
; __device__ __forceinline__ void rg_d3(const Ctx& cx, const Params& p, int l, int idx) {
;     ...
; #pragma unroll
;   for (int i = 0; i < 16; ++i) {
;     float2 au = AU[((size_t)(row0 + i)) * 512 + ch];
;     h = au.x * h + au.y;
;     hf[i] = h;
;   }
;   int n = tb16 < 16 ? 15 - tb16 : 159 - tb16;
;   h = PH[((size_t)(b * 2 + 1) * 144 + n) * 512 + ch].y;
; #pragma unroll
;   for (int s = 0; s < 16; ++s) {
;     int i = 15 - s;
;     float2 au = AU[((size_t)NROW + row0 + i) * 512 + ch];
;     h = au.x * h + au.y;
;     float gz = z[(size_t)(row0 + i) * INW + 6656 + ch];
;     mix[(size_t)(row0 + i) * DM + 1536 + ch] = f2bf(gz * (hf[i] + h));
;   }
	v_fmac_f32_e32 v25, v17, v24
	s_waitcnt vmcnt(19)
	v_fmac_f32_e32 v29, v25, v28
	s_waitcnt vmcnt(18)
	v_fmac_f32_e32 v35, v29, v34
	s_waitcnt vmcnt(17)
	v_fmac_f32_e32 v39, v35, v38
	s_waitcnt vmcnt(16)
	v_fmac_f32_e32 v45, v39, v44
	v_readlane_b32 s10, v252, 37
	s_waitcnt vmcnt(15)
	v_fmac_f32_e32 v49, v45, v48
	v_lshlrev_b32_e32 v62, 1, v110
	v_mov_b32_e32 v63, v18
	v_readlane_b32 s11, v252, 38
	s_movk_i32 s20, 0x7fff
	s_mov_b32 s7, 0x240b000
	s_waitcnt vmcnt(14)
	v_fmac_f32_e32 v55, v49, v54
	v_lshl_add_u64 v[62:63], s[10:11], 0, v[62:63]
	v_lshl_add_u64 v[80:81], v[62:63], 0, v[104:105]
	v_mad_i64_i32 v[82:83], s[10:11], v82, s54, v[66:67]
	v_mad_i64_i32 v[78:79], s[10:11], v78, s54, v[66:67]
	s_waitcnt vmcnt(13)
	v_fmac_f32_e32 v59, v55, v58
	v_mad_i64_i32 v[76:77], s[10:11], v76, s54, v[66:67]
	global_load_dword v10, v[76:77], off nt
	v_mad_i64_i32 v[74:75], s[10:11], v74, s54, v[66:67]
	s_waitcnt vmcnt(13)
	v_fmac_f32_e32 v89, v59, v88
	global_load_dword v16, v[74:75], off nt
	v_mad_i64_i32 v[70:71], s[10:11], v70, s54, v[66:67]
	global_load_dword v24, v[70:71], off nt
	v_mad_i64_i32 v[68:69], s[10:11], v68, s54, v[66:67]
	v_mad_i64_i32 v[64:65], s[10:11], v64, s54, v[66:67]
	s_waitcnt vmcnt(13)
	v_fmac_f32_e32 v95, v89, v94
	global_load_dword v28, v[68:69], off nt
	global_load_dword v34, v[64:65], off nt
	v_lshl_add_u64 v[8:9], v[62:63], 0, v[8:9]
	v_lshl_add_u64 v[4:5], v[62:63], 0, v[4:5]
	v_lshl_add_u64 v[0:1], v[62:63], 0, v[0:1]
	s_waitcnt vmcnt(14)
	v_fmac_f32_e32 v101, v95, v100
	s_waitcnt vmcnt(13)
	v_fmac_f32_e32 v107, v101, v106
	s_waitcnt vmcnt(12)
	v_fmac_f32_e32 v109, v13, v108
	v_add_f32_e32 v2, v107, v109
	v_mad_i64_i32 v[12:13], s[10:11], v12, s54, v[66:67]
	s_waitcnt vmcnt(11)
	v_mul_f32_e32 v2, v31, v2
	v_bfe_u32 v6, v2, 16, 1
	v_add3_u32 v2, v2, v6, s20
	global_store_short_d16_hi v[80:81], v2, off
	v_lshl_add_u64 v[80:81], v[62:63], 0, v[98:99]
	v_mad_i64_i32 v[30:31], s[10:11], v30, s54, v[66:67]
	s_waitcnt vmcnt(11)
	v_fmac_f32_e32 v103, v109, v102
	v_add_f32_e32 v2, v101, v103
	s_waitcnt vmcnt(10)
	v_mul_f32_e32 v2, v41, v2
	v_bfe_u32 v6, v2, 16, 1
	v_add3_u32 v2, v2, v6, s20
	global_store_short_d16_hi v[80:81], v2, off
	v_lshl_add_u64 v[80:81], v[62:63], 0, v[92:93]
	v_mad_i64_i32 v[40:41], s[10:11], v40, s54, v[66:67]
	s_waitcnt vmcnt(10)
	v_fmac_f32_e32 v97, v103, v96
	v_add_f32_e32 v2, v95, v97
	s_waitcnt vmcnt(9)
	v_mul_f32_e32 v2, v53, v2
	v_bfe_u32 v6, v2, 16, 1
	v_add3_u32 v2, v2, v6, s20
	global_store_short_d16_hi v[80:81], v2, off
	v_lshl_add_u64 v[80:81], v[62:63], 0, v[86:87]
	v_mad_i64_i32 v[52:53], s[10:11], v52, s54, v[66:67]
	s_waitcnt vmcnt(9)
	v_fmac_f32_e32 v73, v97, v72
	v_add_f32_e32 v2, v89, v73
	s_waitcnt vmcnt(8)
	v_mul_f32_e32 v2, v61, v2
	v_bfe_u32 v6, v2, 16, 1
	v_add3_u32 v2, v2, v6, s20
	global_store_short_d16_hi v[80:81], v2, off
	v_add_co_u32_e32 v80, vcc, s7, v22
	s_mov_b32 s7, 0x240a000
	s_nop 0
	v_addc_co_u32_e32 v81, vcc, 0, v23, vcc
	global_load_dwordx2 v[80:81], v[80:81], off nt
	v_mad_i64_i32 v[60:61], s[10:11], v60, s54, v[66:67]
	global_load_dword v2, v[82:83], off nt
	global_load_dword v6, v[78:79], off nt
	v_add_co_u32_e32 v82, vcc, s7, v22
	s_mov_b32 s7, 0x2409000
	s_nop 0
	v_addc_co_u32_e32 v83, vcc, 0, v23, vcc
	global_load_dwordx2 v[82:83], v[82:83], off nt
	v_add_co_u32_e32 v78, vcc, s7, v22
	s_mov_b32 s7, 0x2408000
	s_nop 0
	v_addc_co_u32_e32 v79, vcc, 0, v23, vcc
	global_load_dwordx2 v[78:79], v[78:79], off nt
	v_add_co_u32_e32 v76, vcc, s7, v22
	s_mov_b32 s7, 0x2407000
	s_nop 0
	v_addc_co_u32_e32 v77, vcc, 0, v23, vcc
	global_load_dwordx2 v[76:77], v[76:77], off nt
	v_add_co_u32_e32 v74, vcc, s7, v22
	s_mov_b32 s7, 0x2406000
	s_nop 0
	v_addc_co_u32_e32 v75, vcc, 0, v23, vcc
	global_load_dwordx2 v[74:75], v[74:75], off nt
	v_add_co_u32_e32 v70, vcc, s7, v22
	s_mov_b32 s7, 0x2405000
	s_nop 0
	v_addc_co_u32_e32 v71, vcc, 0, v23, vcc
	global_load_dwordx2 v[70:71], v[70:71], off nt
	v_add_co_u32_e32 v68, vcc, s7, v22
	s_mov_b32 s7, 0x2404000
	s_nop 0
	v_addc_co_u32_e32 v69, vcc, 0, v23, vcc
	global_load_dwordx2 v[68:69], v[68:69], off nt
	s_waitcnt vmcnt(8)
; __device__ __forceinline__ void rg_d3(const Ctx& cx, const Params& p, int l, int idx) {
;     ...
; #pragma unroll
;   for (int s = 0; s < 16; ++s) {
;     int i = 15 - s;
;     float2 au = AU[((size_t)NROW + row0 + i) * 512 + ch];
;     h = au.x * h + au.y;
;     float gz = z[(size_t)(row0 + i) * INW + 6656 + ch];
;     mix[(size_t)(row0 + i) * DM + 1536 + ch] = f2bf(gz * (hf[i] + h));
;   }
	v_fmac_f32_e32 v81, v73, v80
	global_load_dword v38, v[60:61], off nt
	global_load_dword v44, v[52:53], off nt
	global_load_dword v48, v[40:41], off nt
	v_add_co_u32_e32 v64, vcc, s7, v22
	s_mov_b32 s7, 0x2403000
	s_nop 0
	v_addc_co_u32_e32 v65, vcc, 0, v23, vcc
	global_load_dwordx2 v[64:65], v[64:65], off nt
	v_add_co_u32_e32 v60, vcc, s7, v22
	s_mov_b32 s7, 0x2402000
	s_nop 0
	v_addc_co_u32_e32 v61, vcc, 0, v23, vcc
	global_load_dwordx2 v[60:61], v[60:61], off nt
	v_add_co_u32_e32 v52, vcc, s7, v22
	global_load_dword v30, v[30:31], off nt
	s_nop 0
	v_addc_co_u32_e32 v53, vcc, 0, v23, vcc
	global_load_dwordx2 v[52:53], v[52:53], off nt
	v_add_co_u32_e32 v40, vcc, 0x2401000, v22
	global_load_dword v31, v[12:13], off nt
	s_nop 0
	v_addc_co_u32_e32 v41, vcc, 0, v23, vcc
	global_load_dwordx2 v[40:41], v[40:41], off nt
	v_add_co_u32_e32 v22, vcc, 0x2400000, v22
	v_add_f32_e32 v12, v59, v81
	s_nop 0
	v_addc_co_u32_e32 v23, vcc, 0, v23, vcc
	global_load_dwordx2 v[22:23], v[22:23], off nt
	s_waitcnt vmcnt(17)
	v_mul_f32_e32 v2, v2, v12
	v_bfe_u32 v12, v2, 16, 1
	v_add3_u32 v2, v2, v12, s20
	v_lshl_add_u64 v[12:13], v[62:63], 0, v[56:57]
	s_waitcnt vmcnt(15)
	v_fmac_f32_e32 v83, v81, v82
	global_store_short_d16_hi v[12:13], v2, off
	v_add_f32_e32 v2, v55, v83
	v_mul_f32_e32 v2, v6, v2
	v_bfe_u32 v6, v2, 16, 1
	v_add3_u32 v2, v2, v6, s20
	v_lshl_add_u64 v[12:13], v[62:63], 0, v[50:51]
	s_waitcnt vmcnt(15)
	v_fmac_f32_e32 v79, v83, v78
	global_store_short_d16_hi v[12:13], v2, off
	v_add_f32_e32 v2, v49, v79
	v_mul_f32_e32 v2, v10, v2
	v_bfe_u32 v6, v2, 16, 1
	v_add3_u32 v2, v2, v6, s20
	v_lshl_add_u64 v[12:13], v[62:63], 0, v[46:47]
	s_waitcnt vmcnt(15)
	v_fmac_f32_e32 v77, v79, v76
	global_store_short_d16_hi v[12:13], v2, off
	v_add_f32_e32 v2, v45, v77
	v_mul_f32_e32 v2, v16, v2
	v_bfe_u32 v6, v2, 16, 1
	v_add3_u32 v2, v2, v6, s20
	v_lshl_add_u64 v[12:13], v[62:63], 0, v[42:43]
	s_waitcnt vmcnt(15)
	v_fmac_f32_e32 v75, v77, v74
	global_store_short_d16_hi v[12:13], v2, off
	v_add_f32_e32 v2, v39, v75
	v_mul_f32_e32 v2, v24, v2
	v_bfe_u32 v6, v2, 16, 1
	v_add3_u32 v2, v2, v6, s20
	v_lshl_add_u64 v[12:13], v[62:63], 0, v[36:37]
	s_waitcnt vmcnt(15)
	v_fmac_f32_e32 v71, v75, v70
	global_store_short_d16_hi v[12:13], v2, off
	v_add_f32_e32 v2, v35, v71
	v_mul_f32_e32 v2, v28, v2
	v_bfe_u32 v6, v2, 16, 1
	v_add3_u32 v2, v2, v6, s20
	v_lshl_add_u64 v[12:13], v[62:63], 0, v[32:33]
	s_waitcnt vmcnt(15)
	v_fmac_f32_e32 v69, v71, v68
	global_store_short_d16_hi v[12:13], v2, off
	v_add_f32_e32 v2, v29, v69
	v_mul_f32_e32 v2, v34, v2
	v_bfe_u32 v6, v2, 16, 1
	v_add3_u32 v2, v2, v6, s20
	v_lshl_add_u64 v[12:13], v[62:63], 0, v[26:27]
	global_store_short_d16_hi v[12:13], v2, off
	v_lshl_add_u64 v[12:13], v[62:63], 0, v[20:21]
	s_waitcnt vmcnt(13)
	v_fmac_f32_e32 v65, v69, v64
	v_add_f32_e32 v2, v25, v65
	v_mul_f32_e32 v2, v38, v2
	v_bfe_u32 v6, v2, 16, 1
	v_add3_u32 v2, v2, v6, s20
	global_store_short_d16_hi v[12:13], v2, off
	s_waitcnt vmcnt(13)
	v_fmac_f32_e32 v61, v65, v60
	v_add_f32_e32 v2, v17, v61
	v_mul_f32_e32 v2, v44, v2
	v_bfe_u32 v6, v2, 16, 1
	v_add3_u32 v2, v2, v6, s20
	v_lshl_add_u64 v[12:13], v[62:63], 0, v[14:15]
	s_waitcnt vmcnt(11)
	v_fmac_f32_e32 v53, v61, v52
	global_store_short_d16_hi v[12:13], v2, off
	v_add_f32_e32 v2, v11, v53
	v_mul_f32_e32 v2, v48, v2
	v_bfe_u32 v6, v2, 16, 1
	v_add3_u32 v2, v2, v6, s20
	s_waitcnt vmcnt(10)
	v_fmac_f32_e32 v41, v53, v40
	global_store_short_d16_hi v[8:9], v2, off
	v_add_f32_e32 v2, v7, v41
	v_mul_f32_e32 v2, v30, v2
	v_bfe_u32 v6, v2, 16, 1
	v_add3_u32 v2, v2, v6, s20
	s_waitcnt vmcnt(10)
	v_fmac_f32_e32 v23, v41, v22
	global_store_short_d16_hi v[4:5], v2, off
	v_add_f32_e32 v2, v3, v23
	v_mul_f32_e32 v2, v31, v2
	v_bfe_u32 v3, v2, 16, 1
	v_add3_u32 v2, v2, v3, s20
	global_store_short_d16_hi v[0:1], v2, off
	s_branch .LBB0_139
